# adds hand-written S5 carry scan: F block staged through LDS by LDS-DMA, 16-bit LDS accesses, wide copy-out (replaces 128 ushort loads + 128 short stores per lane); hardware exp2/sin/cos for the per-la
# baseline (speedup 1.0000x reference)
; #define LAS __attribute__((address_space(3)))
; __device__ __forceinline__ void s5_scan_bg(LAS unsigned char* lds, const S5In P, const bf16_t* F, bf16_t* XB, int b, int g, const int tid) {
;     const int lane = tid & 63, wid = __builtin_amdgcn_readfirstlane(tid >> 6), p = lane;
;     LAS f32x2v* E = (LAS f32x2v*)lds;
;     LAS f32x2v* XI = (LAS f32x2v*)(lds + 16384);
;     float a1r[2], a1i[2], a16r[2], a16i[2];
; #pragma unroll
;     for (int di = 0; di < 2; ++di) { const int gp = (di * 64 + g) * 64 + p;
;         const float dt = expf(P.log_dt[di * 64 + g]); const float lr = P.lam_re[gp], li = P.lam_im[gp];
;         const float mag = expf(lr * dt), ang = li * dt; float ar = mag * cosf(ang), ai = mag * sinf(ang);
; #pragma unroll
;         for (int sq = 0; sq < 4; ++sq) { const float t = ar * ar - ai * ai; ai = 2.f * ar * ai; ar = t; }
;         a1r[di] = ar; a1i[di] = ai;
; #pragma unroll
;         for (int sq = 0; sq < 4; ++sq) { const float t = ar * ar - ai * ai; ai = 2.f * ar * ai; ar = t; }
;         a16r[di] = ar; a16i[di] = ai; }
;     const bf16_t* Fb = F + ((size_t)g * 1024 + b * 256) * 256;
.LBB0_792:
	v_readlane_b32 s4, v254, 33
	v_readlane_b32 s5, v254, 34
	v_readlane_b32 s6, v252, 63
	ds_read_b64 v[160:161], v236 offset:56
	ds_read_b64 v[162:163], v236 offset:64
	ds_read_b64 v[164:165], v236 offset:72
	v_readfirstlane_b32 s26, v147
	s_waitcnt lgkmcnt(0)
	v_readfirstlane_b32 s8, v160
	v_readfirstlane_b32 s9, v161
	v_readfirstlane_b32 s10, v162
	v_readfirstlane_b32 s11, v163
	v_readfirstlane_b32 s12, v164
	v_readfirstlane_b32 s13, v165
	s_nop 3
	s_lshr_b32 s26, s26, 6
	s_and_b32 s14, s6, 7
	s_lshl_b32 s14, s14, 5
	s_lshr_b32 s15, s6, 3
	s_add_i32 s14, s14, s15
	s_and_b32 s15, s14, 3
	s_lshr_b32 s16, s14, 2
	s_lshl_b32 s17, s16, 19
	s_lshl_b32 s18, s15, 17
	s_add_u32 s17, s17, s18
	s_add_u32 s20, s4, 0x7600000
	s_addc_u32 s21, s5, 0
	s_add_u32 s20, s20, s17
	s_addc_u32 s21, s21, 0
	s_add_u32 s24, s4, 0xb600000
	s_addc_u32 s25, s5, 0
	s_add_u32 s24, s24, s17
	s_addc_u32 s25, s25, 0
	v_and_b32_e32 v160, 63, v147
	v_lshlrev_b32_e32 v161, 4, v160
	s_lshl_b32 s27, s26, 14
	v_add_u32_e32 v161, s27, v161
	s_mov_b32 m0, s27
	s_nop 0
	global_load_lds_dwordx4 v161, s[20:21]
	global_load_lds_dwordx4 v161, s[20:21] offset:1024
	global_load_lds_dwordx4 v161, s[20:21] offset:2048
	global_load_lds_dwordx4 v161, s[20:21] offset:3072
	v_add_u32_e32 v161, 0x1000, v161
	s_add_i32 m0, s27, 0x1000
	s_nop 0
	global_load_lds_dwordx4 v161, s[20:21]
	global_load_lds_dwordx4 v161, s[20:21] offset:1024
	global_load_lds_dwordx4 v161, s[20:21] offset:2048
	global_load_lds_dwordx4 v161, s[20:21] offset:3072
	v_add_u32_e32 v161, 0x1000, v161
	s_add_i32 m0, s27, 0x2000
	s_nop 0
	global_load_lds_dwordx4 v161, s[20:21]
	global_load_lds_dwordx4 v161, s[20:21] offset:1024
	global_load_lds_dwordx4 v161, s[20:21] offset:2048
	global_load_lds_dwordx4 v161, s[20:21] offset:3072
	v_add_u32_e32 v161, 0x1000, v161
	s_add_i32 m0, s27, 0x3000
	s_nop 0
	global_load_lds_dwordx4 v161, s[20:21]
	global_load_lds_dwordx4 v161, s[20:21] offset:1024
	global_load_lds_dwordx4 v161, s[20:21] offset:2048
	global_load_lds_dwordx4 v161, s[20:21] offset:3072
	s_lshl_b32 s28, s34, 7
	s_add_i32 s28, s28, s16
	s_lshl_b32 s28, s28, 2
	s_add_u32 s12, s12, s28
	s_addc_u32 s13, s13, 0
	s_load_dword s30, s[12:13], 0x0
	s_load_dword s31, s[12:13], 0x100
	s_lshl_b32 s29, s34, 15
	s_lshl_b32 s28, s16, 8
	s_add_i32 s29, s29, s28
	v_lshlrev_b32_e32 v162, 2, v160
	v_add_u32_e32 v162, s29, v162
	v_add_u32_e32 v163, 0x4000, v162
	global_load_dword v180, v162, s[8:9]
	global_load_dword v181, v163, s[8:9]
	global_load_dword v182, v162, s[10:11]
	global_load_dword v183, v163, s[10:11]
	v_mov_b32_e32 v190, 0x3fb8aa3b
	s_waitcnt lgkmcnt(0)
	v_mul_f32_e32 v184, s30, v190
	v_mul_f32_e32 v185, s31, v190
	v_exp_f32_e32 v184, v184
	v_exp_f32_e32 v185, v185
	s_waitcnt vmcnt(0)
	v_mul_f32_e32 v186, v180, v184
	v_mul_f32_e32 v187, v182, v184
	v_mul_f32_e32 v186, v186, v190
	v_mul_f32_e32 v187, 0.15915494, v187
	v_exp_f32_e32 v186, v186
	v_fract_f32_e32 v187, v187
	s_nop 0
	v_cos_f32_e32 v188, v187
	v_sin_f32_e32 v189, v187
	s_nop 0
	v_mul_f32_e32 v164, v186, v188
	v_mul_f32_e32 v165, v186, v189
	v_mul_f32_e32 v191, v165, v165
	v_mul_f32_e32 v192, v164, v165
	v_fma_f32 v164, v164, v164, -v191
	v_add_f32_e32 v165, v192, v192
	v_mul_f32_e32 v191, v165, v165
	v_mul_f32_e32 v192, v164, v165
	v_fma_f32 v164, v164, v164, -v191
	v_add_f32_e32 v165, v192, v192
	v_mul_f32_e32 v191, v165, v165
	v_mul_f32_e32 v192, v164, v165
	v_fma_f32 v164, v164, v164, -v191
	v_add_f32_e32 v165, v192, v192
	v_mul_f32_e32 v191, v165, v165
	v_mul_f32_e32 v192, v164, v165
	v_fma_f32 v164, v164, v164, -v191
	v_add_f32_e32 v165, v192, v192
	v_mov_b32_e32 v168, v164
	v_mov_b32_e32 v169, v165
	v_mul_f32_e32 v191, v169, v169
	v_mul_f32_e32 v192, v168, v169
	v_fma_f32 v168, v168, v168, -v191
	v_add_f32_e32 v169, v192, v192
	v_mul_f32_e32 v191, v169, v169
	v_mul_f32_e32 v192, v168, v169
	v_fma_f32 v168, v168, v168, -v191
	v_add_f32_e32 v169, v192, v192
	v_mul_f32_e32 v191, v169, v169
	v_mul_f32_e32 v192, v168, v169
	v_fma_f32 v168, v168, v168, -v191
	v_add_f32_e32 v169, v192, v192
	v_mul_f32_e32 v191, v169, v169
	v_mul_f32_e32 v192, v168, v169
	v_fma_f32 v168, v168, v168, -v191
	v_add_f32_e32 v169, v192, v192
	v_mul_f32_e32 v186, v181, v185
	v_mul_f32_e32 v187, v183, v185
	v_mul_f32_e32 v186, v186, v190
	v_mul_f32_e32 v187, 0.15915494, v187
	v_exp_f32_e32 v186, v186
	v_fract_f32_e32 v187, v187
	s_nop 0
	v_cos_f32_e32 v188, v187
	v_sin_f32_e32 v189, v187
	s_nop 0
	v_mul_f32_e32 v166, v186, v188
	v_mul_f32_e32 v167, v186, v189
	v_mul_f32_e32 v191, v167, v167
	v_mul_f32_e32 v192, v166, v167
	v_fma_f32 v166, v166, v166, -v191
	v_add_f32_e32 v167, v192, v192
	v_mul_f32_e32 v191, v167, v167
	v_mul_f32_e32 v192, v166, v167
	v_fma_f32 v166, v166, v166, -v191
	v_add_f32_e32 v167, v192, v192
	v_mul_f32_e32 v191, v167, v167
	v_mul_f32_e32 v192, v166, v167
	v_fma_f32 v166, v166, v166, -v191
	v_add_f32_e32 v167, v192, v192
	v_mul_f32_e32 v191, v167, v167
	v_mul_f32_e32 v192, v166, v167
	v_fma_f32 v166, v166, v166, -v191
	v_add_f32_e32 v167, v192, v192
	v_mov_b32_e32 v170, v166
	v_mov_b32_e32 v171, v167
	v_mul_f32_e32 v191, v171, v171
	v_mul_f32_e32 v192, v170, v171
	v_fma_f32 v170, v170, v170, -v191
	v_add_f32_e32 v171, v192, v192
	v_mul_f32_e32 v191, v171, v171
	v_mul_f32_e32 v192, v170, v171
	v_fma_f32 v170, v170, v170, -v191
	v_add_f32_e32 v171, v192, v192
	v_mul_f32_e32 v191, v171, v171
	v_mul_f32_e32 v192, v170, v171
	v_fma_f32 v170, v170, v170, -v191
	v_add_f32_e32 v171, v192, v192
	v_mul_f32_e32 v191, v171, v171
	v_mul_f32_e32 v192, v170, v171
	v_fma_f32 v170, v170, v170, -v191
	v_add_f32_e32 v171, v192, v192
	s_barrier
; __device__ __forceinline__ float bf2f(bf16_t v) { return __uint_as_float((unsigned)v << 16); }
; __device__ __forceinline__ void s5_scan_bg(LAS unsigned char* lds, const S5In P, const bf16_t* F, bf16_t* XB, int b, int g, const int tid) {
;     ...
;     const bf16_t* Fb = F + ((size_t)g * 1024 + b * 256) * 256;
;     float fr[4][16], fi[4][16];
; #pragma unroll
;     for (int jj = 0; jj < 4; ++jj) { const int job = wid + 8 * jj, di = job >> 4, seg = job & 15;
; #pragma unroll
;         for (int j = 0; j < 16; ++j) { const int c = di == 0 ? seg * 16 + j : 255 - (seg * 16 + j); const bf16_t* fp = Fb + (size_t)c * 256 + di * 128 + p; fr[jj][j] = bf2f(fp[0]); fi[jj][j] = bf2f(fp[64]); } }
	v_lshlrev_b32_e32 v174, 1, v160
	s_lshl_b32 s28, s26, 13
	v_add_u32_e32 v176, s28, v174
	v_add_u32_e32 v177, 0x10000, v176
	s_sub_u32 s29, 0x1e100, s28
	v_add_u32_e32 v178, s29, v174
	v_add_u32_e32 v179, 0xffff0000, v178
	ds_read_u16 v0, v176
	ds_read_u16 v1, v176 offset:128
	ds_read_u16 v2, v176 offset:512
	ds_read_u16 v3, v176 offset:640
	ds_read_u16 v4, v176 offset:1024
	ds_read_u16 v5, v176 offset:1152
	ds_read_u16 v6, v176 offset:1536
	ds_read_u16 v7, v176 offset:1664
	s_waitcnt lgkmcnt(0)
	v_lshlrev_b32_e32 v0, 16, v0
	v_lshlrev_b32_e32 v1, 16, v1
	v_lshlrev_b32_e32 v2, 16, v2
	v_lshlrev_b32_e32 v3, 16, v3
	v_lshlrev_b32_e32 v4, 16, v4
	v_lshlrev_b32_e32 v5, 16, v5
	v_lshlrev_b32_e32 v6, 16, v6
	v_lshlrev_b32_e32 v7, 16, v7
	ds_read_u16 v8, v176 offset:2048
	ds_read_u16 v9, v176 offset:2176
	ds_read_u16 v10, v176 offset:2560
	ds_read_u16 v11, v176 offset:2688
	ds_read_u16 v12, v176 offset:3072
	ds_read_u16 v13, v176 offset:3200
	ds_read_u16 v14, v176 offset:3584
	ds_read_u16 v15, v176 offset:3712
	s_waitcnt lgkmcnt(0)
	v_lshlrev_b32_e32 v8, 16, v8
	v_lshlrev_b32_e32 v9, 16, v9
	v_lshlrev_b32_e32 v10, 16, v10
	v_lshlrev_b32_e32 v11, 16, v11
	v_lshlrev_b32_e32 v12, 16, v12
	v_lshlrev_b32_e32 v13, 16, v13
	v_lshlrev_b32_e32 v14, 16, v14
	v_lshlrev_b32_e32 v15, 16, v15
	ds_read_u16 v16, v176 offset:4096
	ds_read_u16 v17, v176 offset:4224
	ds_read_u16 v18, v176 offset:4608
	ds_read_u16 v19, v176 offset:4736
	ds_read_u16 v20, v176 offset:5120
	ds_read_u16 v21, v176 offset:5248
	ds_read_u16 v22, v176 offset:5632
	ds_read_u16 v23, v176 offset:5760
	s_waitcnt lgkmcnt(0)
	v_lshlrev_b32_e32 v16, 16, v16
	v_lshlrev_b32_e32 v17, 16, v17
	v_lshlrev_b32_e32 v18, 16, v18
	v_lshlrev_b32_e32 v19, 16, v19
	v_lshlrev_b32_e32 v20, 16, v20
	v_lshlrev_b32_e32 v21, 16, v21
	v_lshlrev_b32_e32 v22, 16, v22
	v_lshlrev_b32_e32 v23, 16, v23
	ds_read_u16 v24, v176 offset:6144
	ds_read_u16 v25, v176 offset:6272
	ds_read_u16 v26, v176 offset:6656
	ds_read_u16 v27, v176 offset:6784
	ds_read_u16 v28, v176 offset:7168
	ds_read_u16 v29, v176 offset:7296
	ds_read_u16 v30, v176 offset:7680
	ds_read_u16 v31, v176 offset:7808
	s_waitcnt lgkmcnt(0)
	v_lshlrev_b32_e32 v24, 16, v24
	v_lshlrev_b32_e32 v25, 16, v25
	v_lshlrev_b32_e32 v26, 16, v26
	v_lshlrev_b32_e32 v27, 16, v27
	v_lshlrev_b32_e32 v28, 16, v28
	v_lshlrev_b32_e32 v29, 16, v29
	v_lshlrev_b32_e32 v30, 16, v30
	v_lshlrev_b32_e32 v31, 16, v31
	ds_read_u16 v32, v177
	ds_read_u16 v33, v177 offset:128
	ds_read_u16 v34, v177 offset:512
	ds_read_u16 v35, v177 offset:640
	ds_read_u16 v36, v177 offset:1024
	ds_read_u16 v37, v177 offset:1152
	ds_read_u16 v38, v177 offset:1536
	ds_read_u16 v39, v177 offset:1664
	s_waitcnt lgkmcnt(0)
	v_lshlrev_b32_e32 v32, 16, v32
	v_lshlrev_b32_e32 v33, 16, v33
	v_lshlrev_b32_e32 v34, 16, v34
	v_lshlrev_b32_e32 v35, 16, v35
	v_lshlrev_b32_e32 v36, 16, v36
	v_lshlrev_b32_e32 v37, 16, v37
	v_lshlrev_b32_e32 v38, 16, v38
	v_lshlrev_b32_e32 v39, 16, v39
	ds_read_u16 v40, v177 offset:2048
	ds_read_u16 v41, v177 offset:2176
	ds_read_u16 v42, v177 offset:2560
	ds_read_u16 v43, v177 offset:2688
	ds_read_u16 v44, v177 offset:3072
	ds_read_u16 v45, v177 offset:3200
	ds_read_u16 v46, v177 offset:3584
	ds_read_u16 v47, v177 offset:3712
	s_waitcnt lgkmcnt(0)
	v_lshlrev_b32_e32 v40, 16, v40
	v_lshlrev_b32_e32 v41, 16, v41
	v_lshlrev_b32_e32 v42, 16, v42
	v_lshlrev_b32_e32 v43, 16, v43
	v_lshlrev_b32_e32 v44, 16, v44
	v_lshlrev_b32_e32 v45, 16, v45
	v_lshlrev_b32_e32 v46, 16, v46
	v_lshlrev_b32_e32 v47, 16, v47
	ds_read_u16 v48, v177 offset:4096
	ds_read_u16 v49, v177 offset:4224
	ds_read_u16 v50, v177 offset:4608
	ds_read_u16 v51, v177 offset:4736
	ds_read_u16 v52, v177 offset:5120
	ds_read_u16 v53, v177 offset:5248
	ds_read_u16 v54, v177 offset:5632
	ds_read_u16 v55, v177 offset:5760
	s_waitcnt lgkmcnt(0)
	v_lshlrev_b32_e32 v48, 16, v48
	v_lshlrev_b32_e32 v49, 16, v49
	v_lshlrev_b32_e32 v50, 16, v50
	v_lshlrev_b32_e32 v51, 16, v51
	v_lshlrev_b32_e32 v52, 16, v52
	v_lshlrev_b32_e32 v53, 16, v53
	v_lshlrev_b32_e32 v54, 16, v54
	v_lshlrev_b32_e32 v55, 16, v55
	ds_read_u16 v56, v177 offset:6144
	ds_read_u16 v57, v177 offset:6272
	ds_read_u16 v58, v177 offset:6656
	ds_read_u16 v59, v177 offset:6784
	ds_read_u16 v60, v177 offset:7168
	ds_read_u16 v61, v177 offset:7296
	ds_read_u16 v62, v177 offset:7680
	ds_read_u16 v63, v177 offset:7808
	s_waitcnt lgkmcnt(0)
	v_lshlrev_b32_e32 v56, 16, v56
	v_lshlrev_b32_e32 v57, 16, v57
	v_lshlrev_b32_e32 v58, 16, v58
	v_lshlrev_b32_e32 v59, 16, v59
	v_lshlrev_b32_e32 v60, 16, v60
	v_lshlrev_b32_e32 v61, 16, v61
	v_lshlrev_b32_e32 v62, 16, v62
	v_lshlrev_b32_e32 v63, 16, v63
	ds_read_u16 v64, v178 offset:7680
	ds_read_u16 v65, v178 offset:7808
	ds_read_u16 v66, v178 offset:7168
	ds_read_u16 v67, v178 offset:7296
	ds_read_u16 v68, v178 offset:6656
	ds_read_u16 v69, v178 offset:6784
	ds_read_u16 v70, v178 offset:6144
	ds_read_u16 v71, v178 offset:6272
	s_waitcnt lgkmcnt(0)
	v_lshlrev_b32_e32 v64, 16, v64
	v_lshlrev_b32_e32 v65, 16, v65
	v_lshlrev_b32_e32 v66, 16, v66
	v_lshlrev_b32_e32 v67, 16, v67
	v_lshlrev_b32_e32 v68, 16, v68
	v_lshlrev_b32_e32 v69, 16, v69
	v_lshlrev_b32_e32 v70, 16, v70
	v_lshlrev_b32_e32 v71, 16, v71
	ds_read_u16 v72, v178 offset:5632
	ds_read_u16 v73, v178 offset:5760
	ds_read_u16 v74, v178 offset:5120
	ds_read_u16 v75, v178 offset:5248
	ds_read_u16 v76, v178 offset:4608
	ds_read_u16 v77, v178 offset:4736
	ds_read_u16 v78, v178 offset:4096
	ds_read_u16 v79, v178 offset:4224
	s_waitcnt lgkmcnt(0)
; __device__ __forceinline__ float bf2f(bf16_t v) { return __uint_as_float((unsigned)v << 16); }
; __device__ __forceinline__ void s5_scan_bg(LAS unsigned char* lds, const S5In P, const bf16_t* F, bf16_t* XB, int b, int g, const int tid) {
;     ...
;     const bf16_t* Fb = F + ((size_t)g * 1024 + b * 256) * 256;
;     float fr[4][16], fi[4][16];
; #pragma unroll
;     for (int jj = 0; jj < 4; ++jj) { const int job = wid + 8 * jj, di = job >> 4, seg = job & 15;
; #pragma unroll
;         for (int j = 0; j < 16; ++j) { const int c = di == 0 ? seg * 16 + j : 255 - (seg * 16 + j); const bf16_t* fp = Fb + (size_t)c * 256 + di * 128 + p; fr[jj][j] = bf2f(fp[0]); fi[jj][j] = bf2f(fp[64]); } }
; #pragma unroll
;     for (int jj = 0; jj < 4; ++jj) { const int job = wid + 8 * jj, di = job >> 4, seg = job & 15;
;         const float ar = di ? a1r[1] : a1r[0], ai = di ? a1i[1] : a1i[0]; float xr = 0.f, xi = 0.f;
; #pragma unroll
;         for (int j = 0; j < 16; ++j) { const float nxr = ar * xr - ai * xi + fr[jj][j], nxi = ar * xi + ai * xr + fi[jj][j]; xr = nxr; xi = nxi; }
	v_lshlrev_b32_e32 v72, 16, v72
	v_lshlrev_b32_e32 v73, 16, v73
	v_lshlrev_b32_e32 v74, 16, v74
	v_lshlrev_b32_e32 v75, 16, v75
	v_lshlrev_b32_e32 v76, 16, v76
	v_lshlrev_b32_e32 v77, 16, v77
	v_lshlrev_b32_e32 v78, 16, v78
	v_lshlrev_b32_e32 v79, 16, v79
	ds_read_u16 v80, v178 offset:3584
	ds_read_u16 v81, v178 offset:3712
	ds_read_u16 v82, v178 offset:3072
	ds_read_u16 v83, v178 offset:3200
	ds_read_u16 v84, v178 offset:2560
	ds_read_u16 v85, v178 offset:2688
	ds_read_u16 v86, v178 offset:2048
	ds_read_u16 v87, v178 offset:2176
	s_waitcnt lgkmcnt(0)
	v_lshlrev_b32_e32 v80, 16, v80
	v_lshlrev_b32_e32 v81, 16, v81
	v_lshlrev_b32_e32 v82, 16, v82
	v_lshlrev_b32_e32 v83, 16, v83
	v_lshlrev_b32_e32 v84, 16, v84
	v_lshlrev_b32_e32 v85, 16, v85
	v_lshlrev_b32_e32 v86, 16, v86
	v_lshlrev_b32_e32 v87, 16, v87
	ds_read_u16 v88, v178 offset:1536
	ds_read_u16 v89, v178 offset:1664
	ds_read_u16 v90, v178 offset:1024
	ds_read_u16 v91, v178 offset:1152
	ds_read_u16 v92, v178 offset:512
	ds_read_u16 v93, v178 offset:640
	ds_read_u16 v94, v178
	ds_read_u16 v95, v178 offset:128
	s_waitcnt lgkmcnt(0)
	v_lshlrev_b32_e32 v88, 16, v88
	v_lshlrev_b32_e32 v89, 16, v89
	v_lshlrev_b32_e32 v90, 16, v90
	v_lshlrev_b32_e32 v91, 16, v91
	v_lshlrev_b32_e32 v92, 16, v92
	v_lshlrev_b32_e32 v93, 16, v93
	v_lshlrev_b32_e32 v94, 16, v94
	v_lshlrev_b32_e32 v95, 16, v95
	ds_read_u16 v96, v179 offset:7680
	ds_read_u16 v97, v179 offset:7808
	ds_read_u16 v98, v179 offset:7168
	ds_read_u16 v99, v179 offset:7296
	ds_read_u16 v100, v179 offset:6656
	ds_read_u16 v101, v179 offset:6784
	ds_read_u16 v102, v179 offset:6144
	ds_read_u16 v103, v179 offset:6272
	s_waitcnt lgkmcnt(0)
	v_lshlrev_b32_e32 v96, 16, v96
	v_lshlrev_b32_e32 v97, 16, v97
	v_lshlrev_b32_e32 v98, 16, v98
	v_lshlrev_b32_e32 v99, 16, v99
	v_lshlrev_b32_e32 v100, 16, v100
	v_lshlrev_b32_e32 v101, 16, v101
	v_lshlrev_b32_e32 v102, 16, v102
	v_lshlrev_b32_e32 v103, 16, v103
	ds_read_u16 v104, v179 offset:5632
	ds_read_u16 v105, v179 offset:5760
	ds_read_u16 v106, v179 offset:5120
	ds_read_u16 v107, v179 offset:5248
	ds_read_u16 v108, v179 offset:4608
	ds_read_u16 v109, v179 offset:4736
	ds_read_u16 v110, v179 offset:4096
	ds_read_u16 v111, v179 offset:4224
	s_waitcnt lgkmcnt(0)
	v_lshlrev_b32_e32 v104, 16, v104
	v_lshlrev_b32_e32 v105, 16, v105
	v_lshlrev_b32_e32 v106, 16, v106
	v_lshlrev_b32_e32 v107, 16, v107
	v_lshlrev_b32_e32 v108, 16, v108
	v_lshlrev_b32_e32 v109, 16, v109
	v_lshlrev_b32_e32 v110, 16, v110
	v_lshlrev_b32_e32 v111, 16, v111
	ds_read_u16 v112, v179 offset:3584
	ds_read_u16 v113, v179 offset:3712
	ds_read_u16 v114, v179 offset:3072
	ds_read_u16 v115, v179 offset:3200
	ds_read_u16 v116, v179 offset:2560
	ds_read_u16 v117, v179 offset:2688
	ds_read_u16 v118, v179 offset:2048
	ds_read_u16 v119, v179 offset:2176
	s_waitcnt lgkmcnt(0)
	v_lshlrev_b32_e32 v112, 16, v112
	v_lshlrev_b32_e32 v113, 16, v113
	v_lshlrev_b32_e32 v114, 16, v114
	v_lshlrev_b32_e32 v115, 16, v115
	v_lshlrev_b32_e32 v116, 16, v116
	v_lshlrev_b32_e32 v117, 16, v117
	v_lshlrev_b32_e32 v118, 16, v118
	v_lshlrev_b32_e32 v119, 16, v119
	ds_read_u16 v120, v179 offset:1536
	ds_read_u16 v121, v179 offset:1664
	ds_read_u16 v122, v179 offset:1024
	ds_read_u16 v123, v179 offset:1152
	ds_read_u16 v124, v179 offset:512
	ds_read_u16 v125, v179 offset:640
	ds_read_u16 v126, v179
	ds_read_u16 v127, v179 offset:128
	s_waitcnt lgkmcnt(0)
	v_lshlrev_b32_e32 v120, 16, v120
	v_lshlrev_b32_e32 v121, 16, v121
	v_lshlrev_b32_e32 v122, 16, v122
	v_lshlrev_b32_e32 v123, 16, v123
	v_lshlrev_b32_e32 v124, 16, v124
	v_lshlrev_b32_e32 v125, 16, v125
	v_lshlrev_b32_e32 v126, 16, v126
	v_lshlrev_b32_e32 v127, 16, v127
	v_mov_b32_e32 v180, v0
	v_mov_b32_e32 v181, v1
	v_fma_f32 v191, v164, v180, v2
	v_fma_f32 v192, v164, v181, v3
	v_fma_f32 v193, -v165, v181, v191
	v_fma_f32 v181, v165, v180, v192
	v_mov_b32_e32 v180, v193
	v_fma_f32 v191, v164, v180, v4
	v_fma_f32 v192, v164, v181, v5
	v_fma_f32 v193, -v165, v181, v191
	v_fma_f32 v181, v165, v180, v192
	v_mov_b32_e32 v180, v193
	v_fma_f32 v191, v164, v180, v6
	v_fma_f32 v192, v164, v181, v7
	v_fma_f32 v193, -v165, v181, v191
	v_fma_f32 v181, v165, v180, v192
	v_mov_b32_e32 v180, v193
	v_fma_f32 v191, v164, v180, v8
	v_fma_f32 v192, v164, v181, v9
	v_fma_f32 v193, -v165, v181, v191
	v_fma_f32 v181, v165, v180, v192
	v_mov_b32_e32 v180, v193
	v_fma_f32 v191, v164, v180, v10
	v_fma_f32 v192, v164, v181, v11
	v_fma_f32 v193, -v165, v181, v191
	v_fma_f32 v181, v165, v180, v192
	v_mov_b32_e32 v180, v193
	v_fma_f32 v191, v164, v180, v12
	v_fma_f32 v192, v164, v181, v13
	v_fma_f32 v193, -v165, v181, v191
	v_fma_f32 v181, v165, v180, v192
	v_mov_b32_e32 v180, v193
	v_fma_f32 v191, v164, v180, v14
	v_fma_f32 v192, v164, v181, v15
	v_fma_f32 v193, -v165, v181, v191
	v_fma_f32 v181, v165, v180, v192
	v_mov_b32_e32 v180, v193
	v_fma_f32 v191, v164, v180, v16
	v_fma_f32 v192, v164, v181, v17
	v_fma_f32 v193, -v165, v181, v191
	v_fma_f32 v181, v165, v180, v192
	v_mov_b32_e32 v180, v193
	v_fma_f32 v191, v164, v180, v18
	v_fma_f32 v192, v164, v181, v19
	v_fma_f32 v193, -v165, v181, v191
	v_fma_f32 v181, v165, v180, v192
	v_mov_b32_e32 v180, v193
	v_fma_f32 v191, v164, v180, v20
	v_fma_f32 v192, v164, v181, v21
	v_fma_f32 v193, -v165, v181, v191
	v_fma_f32 v181, v165, v180, v192
	v_mov_b32_e32 v180, v193
	v_fma_f32 v191, v164, v180, v22
	v_fma_f32 v192, v164, v181, v23
	v_fma_f32 v193, -v165, v181, v191
	v_fma_f32 v181, v165, v180, v192
	v_mov_b32_e32 v180, v193
	v_fma_f32 v191, v164, v180, v24
	v_fma_f32 v192, v164, v181, v25
	v_fma_f32 v193, -v165, v181, v191
	v_fma_f32 v181, v165, v180, v192
	v_mov_b32_e32 v180, v193
; __device__ __forceinline__ void s5_scan_bg(LAS unsigned char* lds, const S5In P, const bf16_t* F, bf16_t* XB, int b, int g, const int tid) {
;     ...
; #pragma unroll
;     for (int jj = 0; jj < 4; ++jj) { const int job = wid + 8 * jj, di = job >> 4, seg = job & 15;
;         const float ar = di ? a1r[1] : a1r[0], ai = di ? a1i[1] : a1i[0]; float xr = 0.f, xi = 0.f;
; #pragma unroll
;         for (int j = 0; j < 16; ++j) { const float nxr = ar * xr - ai * xi + fr[jj][j], nxi = ar * xi + ai * xr + fi[jj][j]; xr = nxr; xi = nxi; }
	v_fma_f32 v191, v164, v180, v26
	v_fma_f32 v192, v164, v181, v27
	v_fma_f32 v193, -v165, v181, v191
	v_fma_f32 v181, v165, v180, v192
	v_mov_b32_e32 v180, v193
	v_fma_f32 v191, v164, v180, v28
	v_fma_f32 v192, v164, v181, v29
	v_fma_f32 v193, -v165, v181, v191
	v_fma_f32 v181, v165, v180, v192
	v_mov_b32_e32 v180, v193
	v_fma_f32 v191, v164, v180, v30
	v_fma_f32 v192, v164, v181, v31
	v_fma_f32 v193, -v165, v181, v191
	v_fma_f32 v181, v165, v180, v192
	v_mov_b32_e32 v180, v193
	v_mov_b32_e32 v182, v32
	v_mov_b32_e32 v183, v33
	v_fma_f32 v191, v164, v182, v34
	v_fma_f32 v192, v164, v183, v35
	v_fma_f32 v193, -v165, v183, v191
	v_fma_f32 v183, v165, v182, v192
	v_mov_b32_e32 v182, v193
	v_fma_f32 v191, v164, v182, v36
	v_fma_f32 v192, v164, v183, v37
	v_fma_f32 v193, -v165, v183, v191
	v_fma_f32 v183, v165, v182, v192
	v_mov_b32_e32 v182, v193
	v_fma_f32 v191, v164, v182, v38
	v_fma_f32 v192, v164, v183, v39
	v_fma_f32 v193, -v165, v183, v191
	v_fma_f32 v183, v165, v182, v192
	v_mov_b32_e32 v182, v193
	v_fma_f32 v191, v164, v182, v40
	v_fma_f32 v192, v164, v183, v41
	v_fma_f32 v193, -v165, v183, v191
	v_fma_f32 v183, v165, v182, v192
	v_mov_b32_e32 v182, v193
	v_fma_f32 v191, v164, v182, v42
	v_fma_f32 v192, v164, v183, v43
	v_fma_f32 v193, -v165, v183, v191
	v_fma_f32 v183, v165, v182, v192
	v_mov_b32_e32 v182, v193
	v_fma_f32 v191, v164, v182, v44
	v_fma_f32 v192, v164, v183, v45
	v_fma_f32 v193, -v165, v183, v191
	v_fma_f32 v183, v165, v182, v192
	v_mov_b32_e32 v182, v193
	v_fma_f32 v191, v164, v182, v46
	v_fma_f32 v192, v164, v183, v47
	v_fma_f32 v193, -v165, v183, v191
	v_fma_f32 v183, v165, v182, v192
	v_mov_b32_e32 v182, v193
	v_fma_f32 v191, v164, v182, v48
	v_fma_f32 v192, v164, v183, v49
	v_fma_f32 v193, -v165, v183, v191
	v_fma_f32 v183, v165, v182, v192
	v_mov_b32_e32 v182, v193
	v_fma_f32 v191, v164, v182, v50
	v_fma_f32 v192, v164, v183, v51
	v_fma_f32 v193, -v165, v183, v191
	v_fma_f32 v183, v165, v182, v192
	v_mov_b32_e32 v182, v193
	v_fma_f32 v191, v164, v182, v52
	v_fma_f32 v192, v164, v183, v53
	v_fma_f32 v193, -v165, v183, v191
	v_fma_f32 v183, v165, v182, v192
	v_mov_b32_e32 v182, v193
	v_fma_f32 v191, v164, v182, v54
	v_fma_f32 v192, v164, v183, v55
	v_fma_f32 v193, -v165, v183, v191
	v_fma_f32 v183, v165, v182, v192
	v_mov_b32_e32 v182, v193
	v_fma_f32 v191, v164, v182, v56
	v_fma_f32 v192, v164, v183, v57
	v_fma_f32 v193, -v165, v183, v191
	v_fma_f32 v183, v165, v182, v192
	v_mov_b32_e32 v182, v193
	v_fma_f32 v191, v164, v182, v58
	v_fma_f32 v192, v164, v183, v59
	v_fma_f32 v193, -v165, v183, v191
	v_fma_f32 v183, v165, v182, v192
	v_mov_b32_e32 v182, v193
	v_fma_f32 v191, v164, v182, v60
	v_fma_f32 v192, v164, v183, v61
	v_fma_f32 v193, -v165, v183, v191
	v_fma_f32 v183, v165, v182, v192
	v_mov_b32_e32 v182, v193
	v_fma_f32 v191, v164, v182, v62
	v_fma_f32 v192, v164, v183, v63
	v_fma_f32 v193, -v165, v183, v191
	v_fma_f32 v183, v165, v182, v192
	v_mov_b32_e32 v182, v193
	v_mov_b32_e32 v184, v64
	v_mov_b32_e32 v185, v65
	v_fma_f32 v191, v166, v184, v66
	v_fma_f32 v192, v166, v185, v67
	v_fma_f32 v193, -v167, v185, v191
	v_fma_f32 v185, v167, v184, v192
	v_mov_b32_e32 v184, v193
	v_fma_f32 v191, v166, v184, v68
	v_fma_f32 v192, v166, v185, v69
	v_fma_f32 v193, -v167, v185, v191
	v_fma_f32 v185, v167, v184, v192
	v_mov_b32_e32 v184, v193
	v_fma_f32 v191, v166, v184, v70
	v_fma_f32 v192, v166, v185, v71
	v_fma_f32 v193, -v167, v185, v191
	v_fma_f32 v185, v167, v184, v192
	v_mov_b32_e32 v184, v193
	v_fma_f32 v191, v166, v184, v72
	v_fma_f32 v192, v166, v185, v73
	v_fma_f32 v193, -v167, v185, v191
	v_fma_f32 v185, v167, v184, v192
	v_mov_b32_e32 v184, v193
	v_fma_f32 v191, v166, v184, v74
	v_fma_f32 v192, v166, v185, v75
	v_fma_f32 v193, -v167, v185, v191
	v_fma_f32 v185, v167, v184, v192
	v_mov_b32_e32 v184, v193
	v_fma_f32 v191, v166, v184, v76
	v_fma_f32 v192, v166, v185, v77
	v_fma_f32 v193, -v167, v185, v191
	v_fma_f32 v185, v167, v184, v192
	v_mov_b32_e32 v184, v193
	v_fma_f32 v191, v166, v184, v78
	v_fma_f32 v192, v166, v185, v79
	v_fma_f32 v193, -v167, v185, v191
	v_fma_f32 v185, v167, v184, v192
	v_mov_b32_e32 v184, v193
	v_fma_f32 v191, v166, v184, v80
	v_fma_f32 v192, v166, v185, v81
	v_fma_f32 v193, -v167, v185, v191
	v_fma_f32 v185, v167, v184, v192
	v_mov_b32_e32 v184, v193
	v_fma_f32 v191, v166, v184, v82
	v_fma_f32 v192, v166, v185, v83
	v_fma_f32 v193, -v167, v185, v191
	v_fma_f32 v185, v167, v184, v192
	v_mov_b32_e32 v184, v193
	v_fma_f32 v191, v166, v184, v84
	v_fma_f32 v192, v166, v185, v85
	v_fma_f32 v193, -v167, v185, v191
	v_fma_f32 v185, v167, v184, v192
	v_mov_b32_e32 v184, v193
	v_fma_f32 v191, v166, v184, v86
	v_fma_f32 v192, v166, v185, v87
	v_fma_f32 v193, -v167, v185, v191
	v_fma_f32 v185, v167, v184, v192
	v_mov_b32_e32 v184, v193
	v_fma_f32 v191, v166, v184, v88
	v_fma_f32 v192, v166, v185, v89
	v_fma_f32 v193, -v167, v185, v191
	v_fma_f32 v185, v167, v184, v192
	v_mov_b32_e32 v184, v193
	v_fma_f32 v191, v166, v184, v90
	v_fma_f32 v192, v166, v185, v91
	v_fma_f32 v193, -v167, v185, v191
	v_fma_f32 v185, v167, v184, v192
	v_mov_b32_e32 v184, v193
	v_fma_f32 v191, v166, v184, v92
	v_fma_f32 v192, v166, v185, v93
	v_fma_f32 v193, -v167, v185, v191
	v_fma_f32 v185, v167, v184, v192
	v_mov_b32_e32 v184, v193
	v_fma_f32 v191, v166, v184, v94
	v_fma_f32 v192, v166, v185, v95
	v_fma_f32 v193, -v167, v185, v191
	v_fma_f32 v185, v167, v184, v192
	v_mov_b32_e32 v184, v193
	v_mov_b32_e32 v186, v96
	v_mov_b32_e32 v187, v97
	v_fma_f32 v191, v166, v186, v98
	v_fma_f32 v192, v166, v187, v99
	v_fma_f32 v193, -v167, v187, v191
	v_fma_f32 v187, v167, v186, v192
	v_mov_b32_e32 v186, v193
; #define LDS_WAIT() asm volatile("s_waitcnt lgkmcnt(0)" ::: "memory")
; __device__ __forceinline__ void s5_scan_bg(LAS unsigned char* lds, const S5In P, const bf16_t* F, bf16_t* XB, int b, int g, const int tid) {
;     ...
;     for (int jj = 0; jj < 4; ++jj) { const int job = wid + 8 * jj, di = job >> 4, seg = job & 15;
;         const float ar = di ? a1r[1] : a1r[0], ai = di ? a1i[1] : a1i[0]; float xr = 0.f, xi = 0.f;
; #pragma unroll
;         for (int j = 0; j < 16; ++j) { const float nxr = ar * xr - ai * xi + fr[jj][j], nxi = ar * xi + ai * xr + fi[jj][j]; xr = nxr; xi = nxi; }
;         E[(di * 16 + seg) * 64 + p] = (f32x2v){xr, xi}; }
;     LDS_WAIT(); __syncthreads();
;     if (tid < 128) { const int di = tid >> 6; const float ar = di ? a16r[1] : a16r[0], ai = di ? a16i[1] : a16i[0]; float xr = 0.f, xi = 0.f;
;         for (int seg = 0; seg < 16; ++seg) { XI[(di * 16 + seg) * 64 + p] = (f32x2v){xr, xi}; const f32x2v e = E[(di * 16 + seg) * 64 + p];
;             const float nxr = ar * xr - ai * xi + e.x, nxi = ar * xi + ai * xr + e.y; xr = nxr; xi = nxi; } }
;     LDS_WAIT(); __syncthreads();
	v_fma_f32 v191, v166, v186, v100
	v_fma_f32 v192, v166, v187, v101
	v_fma_f32 v193, -v167, v187, v191
	v_fma_f32 v187, v167, v186, v192
	v_mov_b32_e32 v186, v193
	v_fma_f32 v191, v166, v186, v102
	v_fma_f32 v192, v166, v187, v103
	v_fma_f32 v193, -v167, v187, v191
	v_fma_f32 v187, v167, v186, v192
	v_mov_b32_e32 v186, v193
	v_fma_f32 v191, v166, v186, v104
	v_fma_f32 v192, v166, v187, v105
	v_fma_f32 v193, -v167, v187, v191
	v_fma_f32 v187, v167, v186, v192
	v_mov_b32_e32 v186, v193
	v_fma_f32 v191, v166, v186, v106
	v_fma_f32 v192, v166, v187, v107
	v_fma_f32 v193, -v167, v187, v191
	v_fma_f32 v187, v167, v186, v192
	v_mov_b32_e32 v186, v193
	v_fma_f32 v191, v166, v186, v108
	v_fma_f32 v192, v166, v187, v109
	v_fma_f32 v193, -v167, v187, v191
	v_fma_f32 v187, v167, v186, v192
	v_mov_b32_e32 v186, v193
	v_fma_f32 v191, v166, v186, v110
	v_fma_f32 v192, v166, v187, v111
	v_fma_f32 v193, -v167, v187, v191
	v_fma_f32 v187, v167, v186, v192
	v_mov_b32_e32 v186, v193
	v_fma_f32 v191, v166, v186, v112
	v_fma_f32 v192, v166, v187, v113
	v_fma_f32 v193, -v167, v187, v191
	v_fma_f32 v187, v167, v186, v192
	v_mov_b32_e32 v186, v193
	v_fma_f32 v191, v166, v186, v114
	v_fma_f32 v192, v166, v187, v115
	v_fma_f32 v193, -v167, v187, v191
	v_fma_f32 v187, v167, v186, v192
	v_mov_b32_e32 v186, v193
	v_fma_f32 v191, v166, v186, v116
	v_fma_f32 v192, v166, v187, v117
	v_fma_f32 v193, -v167, v187, v191
	v_fma_f32 v187, v167, v186, v192
	v_mov_b32_e32 v186, v193
	v_fma_f32 v191, v166, v186, v118
	v_fma_f32 v192, v166, v187, v119
	v_fma_f32 v193, -v167, v187, v191
	v_fma_f32 v187, v167, v186, v192
	v_mov_b32_e32 v186, v193
	v_fma_f32 v191, v166, v186, v120
	v_fma_f32 v192, v166, v187, v121
	v_fma_f32 v193, -v167, v187, v191
	v_fma_f32 v187, v167, v186, v192
	v_mov_b32_e32 v186, v193
	v_fma_f32 v191, v166, v186, v122
	v_fma_f32 v192, v166, v187, v123
	v_fma_f32 v193, -v167, v187, v191
	v_fma_f32 v187, v167, v186, v192
	v_mov_b32_e32 v186, v193
	v_fma_f32 v191, v166, v186, v124
	v_fma_f32 v192, v166, v187, v125
	v_fma_f32 v193, -v167, v187, v191
	v_fma_f32 v187, v167, v186, v192
	v_mov_b32_e32 v186, v193
	v_fma_f32 v191, v166, v186, v126
	v_fma_f32 v192, v166, v187, v127
	v_fma_f32 v193, -v167, v187, v191
	v_fma_f32 v187, v167, v186, v192
	v_mov_b32_e32 v186, v193
	s_barrier
	v_lshlrev_b32_e32 v175, 3, v160
	s_lshl_b32 s28, s26, 9
	v_add_u32_e32 v175, s28, v175
	ds_write_b64 v175, v[180:181]
	ds_write_b64 v175, v[182:183] offset:4096
	ds_write_b64 v175, v[184:185] offset:8192
	ds_write_b64 v175, v[186:187] offset:12288
	s_waitcnt lgkmcnt(0)
	s_barrier
	s_cmp_lt_u32 s26, 2
	s_cbranch_scc0 .Ls5scan_comb_done
	s_cmp_eq_u32 s26, 0
	s_cselect_b64 s[36:37], -1, 0
	v_cndmask_b32_e64 v194, v170, v168, s[36:37]
	v_cndmask_b32_e64 v195, v171, v169, s[36:37]
	v_lshlrev_b32_e32 v196, 3, v160
	s_lshl_b32 s28, s26, 13
	v_add_u32_e32 v196, s28, v196
	v_mov_b32_e32 v198, 0
	v_mov_b32_e32 v199, 0
	ds_read_b64 v[200:201], v196
	s_waitcnt lgkmcnt(0)
	ds_write_b64 v196, v[198:199]
	v_fma_f32 v191, v194, v198, v200
	v_fma_f32 v192, v194, v199, v201
	v_fma_f32 v191, -v195, v199, v191
	v_fma_f32 v199, v195, v198, v192
	v_mov_b32_e32 v198, v191
	ds_read_b64 v[200:201], v196 offset:512
	s_waitcnt lgkmcnt(0)
	ds_write_b64 v196, v[198:199] offset:512
	v_fma_f32 v191, v194, v198, v200
	v_fma_f32 v192, v194, v199, v201
	v_fma_f32 v191, -v195, v199, v191
	v_fma_f32 v199, v195, v198, v192
	v_mov_b32_e32 v198, v191
	ds_read_b64 v[200:201], v196 offset:1024
	s_waitcnt lgkmcnt(0)
	ds_write_b64 v196, v[198:199] offset:1024
	v_fma_f32 v191, v194, v198, v200
	v_fma_f32 v192, v194, v199, v201
	v_fma_f32 v191, -v195, v199, v191
	v_fma_f32 v199, v195, v198, v192
	v_mov_b32_e32 v198, v191
	ds_read_b64 v[200:201], v196 offset:1536
	s_waitcnt lgkmcnt(0)
	ds_write_b64 v196, v[198:199] offset:1536
	v_fma_f32 v191, v194, v198, v200
	v_fma_f32 v192, v194, v199, v201
	v_fma_f32 v191, -v195, v199, v191
	v_fma_f32 v199, v195, v198, v192
	v_mov_b32_e32 v198, v191
	ds_read_b64 v[200:201], v196 offset:2048
	s_waitcnt lgkmcnt(0)
	ds_write_b64 v196, v[198:199] offset:2048
	v_fma_f32 v191, v194, v198, v200
	v_fma_f32 v192, v194, v199, v201
	v_fma_f32 v191, -v195, v199, v191
	v_fma_f32 v199, v195, v198, v192
	v_mov_b32_e32 v198, v191
	ds_read_b64 v[200:201], v196 offset:2560
	s_waitcnt lgkmcnt(0)
	ds_write_b64 v196, v[198:199] offset:2560
	v_fma_f32 v191, v194, v198, v200
	v_fma_f32 v192, v194, v199, v201
	v_fma_f32 v191, -v195, v199, v191
	v_fma_f32 v199, v195, v198, v192
	v_mov_b32_e32 v198, v191
	ds_read_b64 v[200:201], v196 offset:3072
	s_waitcnt lgkmcnt(0)
	ds_write_b64 v196, v[198:199] offset:3072
	v_fma_f32 v191, v194, v198, v200
	v_fma_f32 v192, v194, v199, v201
	v_fma_f32 v191, -v195, v199, v191
	v_fma_f32 v199, v195, v198, v192
	v_mov_b32_e32 v198, v191
	ds_read_b64 v[200:201], v196 offset:3584
	s_waitcnt lgkmcnt(0)
	ds_write_b64 v196, v[198:199] offset:3584
	v_fma_f32 v191, v194, v198, v200
	v_fma_f32 v192, v194, v199, v201
	v_fma_f32 v191, -v195, v199, v191
	v_fma_f32 v199, v195, v198, v192
	v_mov_b32_e32 v198, v191
	ds_read_b64 v[200:201], v196 offset:4096
	s_waitcnt lgkmcnt(0)
	ds_write_b64 v196, v[198:199] offset:4096
	v_fma_f32 v191, v194, v198, v200
	v_fma_f32 v192, v194, v199, v201
	v_fma_f32 v191, -v195, v199, v191
	v_fma_f32 v199, v195, v198, v192
	v_mov_b32_e32 v198, v191
	ds_read_b64 v[200:201], v196 offset:4608
	s_waitcnt lgkmcnt(0)
	ds_write_b64 v196, v[198:199] offset:4608
	v_fma_f32 v191, v194, v198, v200
	v_fma_f32 v192, v194, v199, v201
	v_fma_f32 v191, -v195, v199, v191
	v_fma_f32 v199, v195, v198, v192
	v_mov_b32_e32 v198, v191
	ds_read_b64 v[200:201], v196 offset:5120
	s_waitcnt lgkmcnt(0)
; __device__ __forceinline__ unsigned f2bf(float f) { unsigned u = __float_as_uint(f); return (u + 0x7fffu + ((u >> 16) & 1u)) >> 16; }
; #define LDS_WAIT() asm volatile("s_waitcnt lgkmcnt(0)" ::: "memory")
; __device__ __forceinline__ void s5_scan_bg(LAS unsigned char* lds, const S5In P, const bf16_t* F, bf16_t* XB, int b, int g, const int tid) {
;     ...
;     if (tid < 128) { const int di = tid >> 6; const float ar = di ? a16r[1] : a16r[0], ai = di ? a16i[1] : a16i[0]; float xr = 0.f, xi = 0.f;
;         for (int seg = 0; seg < 16; ++seg) { XI[(di * 16 + seg) * 64 + p] = (f32x2v){xr, xi}; const f32x2v e = E[(di * 16 + seg) * 64 + p];
;             const float nxr = ar * xr - ai * xi + e.x, nxi = ar * xi + ai * xr + e.y; xr = nxr; xi = nxi; } }
;     LDS_WAIT(); __syncthreads();
; #pragma unroll
;     for (int jj = 0; jj < 4; ++jj) { const int job = wid + 8 * jj, di = job >> 4, seg = job & 15;
;         const float ar = di ? a1r[1] : a1r[0], ai = di ? a1i[1] : a1i[0]; const f32x2v x0 = XI[(di * 16 + seg) * 64 + p]; float xr = x0.x, xi = x0.y;
;         bf16_t* xg = XB + ((size_t)g * 1024 + b * 256) * 256 + di * 128 + p;
; #pragma unroll
;         for (int j = 0; j < 16; ++j) { const int c = di == 0 ? seg * 16 + j : 255 - (seg * 16 + j);
;             xg[(size_t)c * 256] = (bf16_t)f2bf(xr); xg[(size_t)c * 256 + 64] = (bf16_t)f2bf(xi);
;             const float nxr = ar * xr - ai * xi + fr[jj][j], nxi = ar * xi + ai * xr + fi[jj][j]; xr = nxr; xi = nxi; } }
	ds_write_b64 v196, v[198:199] offset:5120
	v_fma_f32 v191, v194, v198, v200
	v_fma_f32 v192, v194, v199, v201
	v_fma_f32 v191, -v195, v199, v191
	v_fma_f32 v199, v195, v198, v192
	v_mov_b32_e32 v198, v191
	ds_read_b64 v[200:201], v196 offset:5632
	s_waitcnt lgkmcnt(0)
	ds_write_b64 v196, v[198:199] offset:5632
	v_fma_f32 v191, v194, v198, v200
	v_fma_f32 v192, v194, v199, v201
	v_fma_f32 v191, -v195, v199, v191
	v_fma_f32 v199, v195, v198, v192
	v_mov_b32_e32 v198, v191
	ds_read_b64 v[200:201], v196 offset:6144
	s_waitcnt lgkmcnt(0)
	ds_write_b64 v196, v[198:199] offset:6144
	v_fma_f32 v191, v194, v198, v200
	v_fma_f32 v192, v194, v199, v201
	v_fma_f32 v191, -v195, v199, v191
	v_fma_f32 v199, v195, v198, v192
	v_mov_b32_e32 v198, v191
	ds_read_b64 v[200:201], v196 offset:6656
	s_waitcnt lgkmcnt(0)
	ds_write_b64 v196, v[198:199] offset:6656
	v_fma_f32 v191, v194, v198, v200
	v_fma_f32 v192, v194, v199, v201
	v_fma_f32 v191, -v195, v199, v191
	v_fma_f32 v199, v195, v198, v192
	v_mov_b32_e32 v198, v191
	ds_read_b64 v[200:201], v196 offset:7168
	s_waitcnt lgkmcnt(0)
	ds_write_b64 v196, v[198:199] offset:7168
	v_fma_f32 v191, v194, v198, v200
	v_fma_f32 v192, v194, v199, v201
	v_fma_f32 v191, -v195, v199, v191
	v_fma_f32 v199, v195, v198, v192
	v_mov_b32_e32 v198, v191
	ds_read_b64 v[200:201], v196 offset:7680
	s_waitcnt lgkmcnt(0)
	ds_write_b64 v196, v[198:199] offset:7680
	v_fma_f32 v191, v194, v198, v200
	v_fma_f32 v192, v194, v199, v201
	v_fma_f32 v191, -v195, v199, v191
	v_fma_f32 v199, v195, v198, v192
	v_mov_b32_e32 v198, v191
	s_waitcnt lgkmcnt(0)
.Ls5scan_comb_done:
	s_barrier
	ds_read_b64 v[180:181], v175
	ds_read_b64 v[182:183], v175 offset:4096
	ds_read_b64 v[184:185], v175 offset:8192
	ds_read_b64 v[186:187], v175 offset:12288
	s_waitcnt lgkmcnt(0)
	s_barrier
	v_cvt_pk_bf16_f32 v194, v180, v181
	v_fma_f32 v191, v164, v180, v0
	ds_write_b16 v176, v194
	ds_write_b16_d16_hi v176, v194 offset:128
	v_fma_f32 v192, v164, v181, v1
	v_fma_f32 v193, -v165, v181, v191
	v_fma_f32 v181, v165, v180, v192
	v_mov_b32_e32 v180, v193
	v_cvt_pk_bf16_f32 v194, v180, v181
	v_fma_f32 v191, v164, v180, v2
	ds_write_b16 v176, v194 offset:512
	ds_write_b16_d16_hi v176, v194 offset:640
	v_fma_f32 v192, v164, v181, v3
	v_fma_f32 v193, -v165, v181, v191
	v_fma_f32 v181, v165, v180, v192
	v_mov_b32_e32 v180, v193
	v_cvt_pk_bf16_f32 v194, v180, v181
	v_fma_f32 v191, v164, v180, v4
	ds_write_b16 v176, v194 offset:1024
	ds_write_b16_d16_hi v176, v194 offset:1152
	v_fma_f32 v192, v164, v181, v5
	v_fma_f32 v193, -v165, v181, v191
	v_fma_f32 v181, v165, v180, v192
	v_mov_b32_e32 v180, v193
	v_cvt_pk_bf16_f32 v194, v180, v181
	v_fma_f32 v191, v164, v180, v6
	ds_write_b16 v176, v194 offset:1536
	ds_write_b16_d16_hi v176, v194 offset:1664
	v_fma_f32 v192, v164, v181, v7
	v_fma_f32 v193, -v165, v181, v191
	v_fma_f32 v181, v165, v180, v192
	v_mov_b32_e32 v180, v193
	v_cvt_pk_bf16_f32 v194, v180, v181
	v_fma_f32 v191, v164, v180, v8
	ds_write_b16 v176, v194 offset:2048
	ds_write_b16_d16_hi v176, v194 offset:2176
	v_fma_f32 v192, v164, v181, v9
	v_fma_f32 v193, -v165, v181, v191
	v_fma_f32 v181, v165, v180, v192
	v_mov_b32_e32 v180, v193
	v_cvt_pk_bf16_f32 v194, v180, v181
	v_fma_f32 v191, v164, v180, v10
	ds_write_b16 v176, v194 offset:2560
	ds_write_b16_d16_hi v176, v194 offset:2688
	v_fma_f32 v192, v164, v181, v11
	v_fma_f32 v193, -v165, v181, v191
	v_fma_f32 v181, v165, v180, v192
	v_mov_b32_e32 v180, v193
	v_cvt_pk_bf16_f32 v194, v180, v181
	v_fma_f32 v191, v164, v180, v12
	ds_write_b16 v176, v194 offset:3072
	ds_write_b16_d16_hi v176, v194 offset:3200
	v_fma_f32 v192, v164, v181, v13
	v_fma_f32 v193, -v165, v181, v191
	v_fma_f32 v181, v165, v180, v192
	v_mov_b32_e32 v180, v193
	v_cvt_pk_bf16_f32 v194, v180, v181
	v_fma_f32 v191, v164, v180, v14
	ds_write_b16 v176, v194 offset:3584
	ds_write_b16_d16_hi v176, v194 offset:3712
	v_fma_f32 v192, v164, v181, v15
	v_fma_f32 v193, -v165, v181, v191
	v_fma_f32 v181, v165, v180, v192
	v_mov_b32_e32 v180, v193
	v_cvt_pk_bf16_f32 v194, v180, v181
	v_fma_f32 v191, v164, v180, v16
	ds_write_b16 v176, v194 offset:4096
	ds_write_b16_d16_hi v176, v194 offset:4224
	v_fma_f32 v192, v164, v181, v17
	v_fma_f32 v193, -v165, v181, v191
	v_fma_f32 v181, v165, v180, v192
	v_mov_b32_e32 v180, v193
	v_cvt_pk_bf16_f32 v194, v180, v181
	v_fma_f32 v191, v164, v180, v18
	ds_write_b16 v176, v194 offset:4608
	ds_write_b16_d16_hi v176, v194 offset:4736
	v_fma_f32 v192, v164, v181, v19
	v_fma_f32 v193, -v165, v181, v191
	v_fma_f32 v181, v165, v180, v192
	v_mov_b32_e32 v180, v193
	v_cvt_pk_bf16_f32 v194, v180, v181
	v_fma_f32 v191, v164, v180, v20
	ds_write_b16 v176, v194 offset:5120
	ds_write_b16_d16_hi v176, v194 offset:5248
	v_fma_f32 v192, v164, v181, v21
	v_fma_f32 v193, -v165, v181, v191
	v_fma_f32 v181, v165, v180, v192
	v_mov_b32_e32 v180, v193
	v_cvt_pk_bf16_f32 v194, v180, v181
	v_fma_f32 v191, v164, v180, v22
	ds_write_b16 v176, v194 offset:5632
	ds_write_b16_d16_hi v176, v194 offset:5760
	v_fma_f32 v192, v164, v181, v23
	v_fma_f32 v193, -v165, v181, v191
	v_fma_f32 v181, v165, v180, v192
	v_mov_b32_e32 v180, v193
	v_cvt_pk_bf16_f32 v194, v180, v181
	v_fma_f32 v191, v164, v180, v24
	ds_write_b16 v176, v194 offset:6144
	ds_write_b16_d16_hi v176, v194 offset:6272
	v_fma_f32 v192, v164, v181, v25
	v_fma_f32 v193, -v165, v181, v191
	v_fma_f32 v181, v165, v180, v192
	v_mov_b32_e32 v180, v193
	v_cvt_pk_bf16_f32 v194, v180, v181
	v_fma_f32 v191, v164, v180, v26
	ds_write_b16 v176, v194 offset:6656
	ds_write_b16_d16_hi v176, v194 offset:6784
	v_fma_f32 v192, v164, v181, v27
	v_fma_f32 v193, -v165, v181, v191
	v_fma_f32 v181, v165, v180, v192
; __device__ __forceinline__ unsigned f2bf(float f) { unsigned u = __float_as_uint(f); return (u + 0x7fffu + ((u >> 16) & 1u)) >> 16; }
; __device__ __forceinline__ void s5_scan_bg(LAS unsigned char* lds, const S5In P, const bf16_t* F, bf16_t* XB, int b, int g, const int tid) {
;     ...
;     for (int jj = 0; jj < 4; ++jj) { const int job = wid + 8 * jj, di = job >> 4, seg = job & 15;
;         const float ar = di ? a1r[1] : a1r[0], ai = di ? a1i[1] : a1i[0]; const f32x2v x0 = XI[(di * 16 + seg) * 64 + p]; float xr = x0.x, xi = x0.y;
;         bf16_t* xg = XB + ((size_t)g * 1024 + b * 256) * 256 + di * 128 + p;
; #pragma unroll
;         for (int j = 0; j < 16; ++j) { const int c = di == 0 ? seg * 16 + j : 255 - (seg * 16 + j);
;             xg[(size_t)c * 256] = (bf16_t)f2bf(xr); xg[(size_t)c * 256 + 64] = (bf16_t)f2bf(xi);
;             const float nxr = ar * xr - ai * xi + fr[jj][j], nxi = ar * xi + ai * xr + fi[jj][j]; xr = nxr; xi = nxi; } }
	v_mov_b32_e32 v180, v193
	v_cvt_pk_bf16_f32 v194, v180, v181
	v_fma_f32 v191, v164, v180, v28
	ds_write_b16 v176, v194 offset:7168
	ds_write_b16_d16_hi v176, v194 offset:7296
	v_fma_f32 v192, v164, v181, v29
	v_fma_f32 v193, -v165, v181, v191
	v_fma_f32 v181, v165, v180, v192
	v_mov_b32_e32 v180, v193
	v_cvt_pk_bf16_f32 v194, v180, v181
	v_fma_f32 v191, v164, v180, v30
	ds_write_b16 v176, v194 offset:7680
	ds_write_b16_d16_hi v176, v194 offset:7808
	v_fma_f32 v192, v164, v181, v31
	v_fma_f32 v193, -v165, v181, v191
	v_fma_f32 v181, v165, v180, v192
	v_mov_b32_e32 v180, v193
	v_cvt_pk_bf16_f32 v194, v182, v183
	v_fma_f32 v191, v164, v182, v32
	ds_write_b16 v177, v194
	ds_write_b16_d16_hi v177, v194 offset:128
	v_fma_f32 v192, v164, v183, v33
	v_fma_f32 v193, -v165, v183, v191
	v_fma_f32 v183, v165, v182, v192
	v_mov_b32_e32 v182, v193
	v_cvt_pk_bf16_f32 v194, v182, v183
	v_fma_f32 v191, v164, v182, v34
	ds_write_b16 v177, v194 offset:512
	ds_write_b16_d16_hi v177, v194 offset:640
	v_fma_f32 v192, v164, v183, v35
	v_fma_f32 v193, -v165, v183, v191
	v_fma_f32 v183, v165, v182, v192
	v_mov_b32_e32 v182, v193
	v_cvt_pk_bf16_f32 v194, v182, v183
	v_fma_f32 v191, v164, v182, v36
	ds_write_b16 v177, v194 offset:1024
	ds_write_b16_d16_hi v177, v194 offset:1152
	v_fma_f32 v192, v164, v183, v37
	v_fma_f32 v193, -v165, v183, v191
	v_fma_f32 v183, v165, v182, v192
	v_mov_b32_e32 v182, v193
	v_cvt_pk_bf16_f32 v194, v182, v183
	v_fma_f32 v191, v164, v182, v38
	ds_write_b16 v177, v194 offset:1536
	ds_write_b16_d16_hi v177, v194 offset:1664
	v_fma_f32 v192, v164, v183, v39
	v_fma_f32 v193, -v165, v183, v191
	v_fma_f32 v183, v165, v182, v192
	v_mov_b32_e32 v182, v193
	v_cvt_pk_bf16_f32 v194, v182, v183
	v_fma_f32 v191, v164, v182, v40
	ds_write_b16 v177, v194 offset:2048
	ds_write_b16_d16_hi v177, v194 offset:2176
	v_fma_f32 v192, v164, v183, v41
	v_fma_f32 v193, -v165, v183, v191
	v_fma_f32 v183, v165, v182, v192
	v_mov_b32_e32 v182, v193
	v_cvt_pk_bf16_f32 v194, v182, v183
	v_fma_f32 v191, v164, v182, v42
	ds_write_b16 v177, v194 offset:2560
	ds_write_b16_d16_hi v177, v194 offset:2688
	v_fma_f32 v192, v164, v183, v43
	v_fma_f32 v193, -v165, v183, v191
	v_fma_f32 v183, v165, v182, v192
	v_mov_b32_e32 v182, v193
	v_cvt_pk_bf16_f32 v194, v182, v183
	v_fma_f32 v191, v164, v182, v44
	ds_write_b16 v177, v194 offset:3072
	ds_write_b16_d16_hi v177, v194 offset:3200
	v_fma_f32 v192, v164, v183, v45
	v_fma_f32 v193, -v165, v183, v191
	v_fma_f32 v183, v165, v182, v192
	v_mov_b32_e32 v182, v193
	v_cvt_pk_bf16_f32 v194, v182, v183
	v_fma_f32 v191, v164, v182, v46
	ds_write_b16 v177, v194 offset:3584
	ds_write_b16_d16_hi v177, v194 offset:3712
	v_fma_f32 v192, v164, v183, v47
	v_fma_f32 v193, -v165, v183, v191
	v_fma_f32 v183, v165, v182, v192
	v_mov_b32_e32 v182, v193
	v_cvt_pk_bf16_f32 v194, v182, v183
	v_fma_f32 v191, v164, v182, v48
	ds_write_b16 v177, v194 offset:4096
	ds_write_b16_d16_hi v177, v194 offset:4224
	v_fma_f32 v192, v164, v183, v49
	v_fma_f32 v193, -v165, v183, v191
	v_fma_f32 v183, v165, v182, v192
	v_mov_b32_e32 v182, v193
	v_cvt_pk_bf16_f32 v194, v182, v183
	v_fma_f32 v191, v164, v182, v50
	ds_write_b16 v177, v194 offset:4608
	ds_write_b16_d16_hi v177, v194 offset:4736
	v_fma_f32 v192, v164, v183, v51
	v_fma_f32 v193, -v165, v183, v191
	v_fma_f32 v183, v165, v182, v192
	v_mov_b32_e32 v182, v193
	v_cvt_pk_bf16_f32 v194, v182, v183
	v_fma_f32 v191, v164, v182, v52
	ds_write_b16 v177, v194 offset:5120
	ds_write_b16_d16_hi v177, v194 offset:5248
	v_fma_f32 v192, v164, v183, v53
	v_fma_f32 v193, -v165, v183, v191
	v_fma_f32 v183, v165, v182, v192
	v_mov_b32_e32 v182, v193
	v_cvt_pk_bf16_f32 v194, v182, v183
	v_fma_f32 v191, v164, v182, v54
	ds_write_b16 v177, v194 offset:5632
	ds_write_b16_d16_hi v177, v194 offset:5760
	v_fma_f32 v192, v164, v183, v55
	v_fma_f32 v193, -v165, v183, v191
	v_fma_f32 v183, v165, v182, v192
	v_mov_b32_e32 v182, v193
	v_cvt_pk_bf16_f32 v194, v182, v183
	v_fma_f32 v191, v164, v182, v56
	ds_write_b16 v177, v194 offset:6144
	ds_write_b16_d16_hi v177, v194 offset:6272
	v_fma_f32 v192, v164, v183, v57
	v_fma_f32 v193, -v165, v183, v191
	v_fma_f32 v183, v165, v182, v192
	v_mov_b32_e32 v182, v193
	v_cvt_pk_bf16_f32 v194, v182, v183
	v_fma_f32 v191, v164, v182, v58
	ds_write_b16 v177, v194 offset:6656
	ds_write_b16_d16_hi v177, v194 offset:6784
	v_fma_f32 v192, v164, v183, v59
	v_fma_f32 v193, -v165, v183, v191
	v_fma_f32 v183, v165, v182, v192
	v_mov_b32_e32 v182, v193
	v_cvt_pk_bf16_f32 v194, v182, v183
	v_fma_f32 v191, v164, v182, v60
	ds_write_b16 v177, v194 offset:7168
	ds_write_b16_d16_hi v177, v194 offset:7296
	v_fma_f32 v192, v164, v183, v61
	v_fma_f32 v193, -v165, v183, v191
	v_fma_f32 v183, v165, v182, v192
	v_mov_b32_e32 v182, v193
	v_cvt_pk_bf16_f32 v194, v182, v183
	v_fma_f32 v191, v164, v182, v62
	ds_write_b16 v177, v194 offset:7680
	ds_write_b16_d16_hi v177, v194 offset:7808
	v_fma_f32 v192, v164, v183, v63
	v_fma_f32 v193, -v165, v183, v191
	v_fma_f32 v183, v165, v182, v192
	v_mov_b32_e32 v182, v193
	v_cvt_pk_bf16_f32 v194, v184, v185
	v_fma_f32 v191, v166, v184, v64
	ds_write_b16 v178, v194 offset:7680
	ds_write_b16_d16_hi v178, v194 offset:7808
	v_fma_f32 v192, v166, v185, v65
	v_fma_f32 v193, -v167, v185, v191
	v_fma_f32 v185, v167, v184, v192
	v_mov_b32_e32 v184, v193
	v_cvt_pk_bf16_f32 v194, v184, v185
	v_fma_f32 v191, v166, v184, v66
	ds_write_b16 v178, v194 offset:7168
	ds_write_b16_d16_hi v178, v194 offset:7296
	v_fma_f32 v192, v166, v185, v67
	v_fma_f32 v193, -v167, v185, v191
	v_fma_f32 v185, v167, v184, v192
	v_mov_b32_e32 v184, v193
	v_cvt_pk_bf16_f32 v194, v184, v185
	v_fma_f32 v191, v166, v184, v68
; __device__ __forceinline__ unsigned f2bf(float f) { unsigned u = __float_as_uint(f); return (u + 0x7fffu + ((u >> 16) & 1u)) >> 16; }
; __device__ __forceinline__ void s5_scan_bg(LAS unsigned char* lds, const S5In P, const bf16_t* F, bf16_t* XB, int b, int g, const int tid) {
;     ...
;     for (int jj = 0; jj < 4; ++jj) { const int job = wid + 8 * jj, di = job >> 4, seg = job & 15;
;         const float ar = di ? a1r[1] : a1r[0], ai = di ? a1i[1] : a1i[0]; const f32x2v x0 = XI[(di * 16 + seg) * 64 + p]; float xr = x0.x, xi = x0.y;
;         bf16_t* xg = XB + ((size_t)g * 1024 + b * 256) * 256 + di * 128 + p;
; #pragma unroll
;         for (int j = 0; j < 16; ++j) { const int c = di == 0 ? seg * 16 + j : 255 - (seg * 16 + j);
;             xg[(size_t)c * 256] = (bf16_t)f2bf(xr); xg[(size_t)c * 256 + 64] = (bf16_t)f2bf(xi);
;             const float nxr = ar * xr - ai * xi + fr[jj][j], nxi = ar * xi + ai * xr + fi[jj][j]; xr = nxr; xi = nxi; } }
	ds_write_b16 v178, v194 offset:6656
	ds_write_b16_d16_hi v178, v194 offset:6784
	v_fma_f32 v192, v166, v185, v69
	v_fma_f32 v193, -v167, v185, v191
	v_fma_f32 v185, v167, v184, v192
	v_mov_b32_e32 v184, v193
	v_cvt_pk_bf16_f32 v194, v184, v185
	v_fma_f32 v191, v166, v184, v70
	ds_write_b16 v178, v194 offset:6144
	ds_write_b16_d16_hi v178, v194 offset:6272
	v_fma_f32 v192, v166, v185, v71
	v_fma_f32 v193, -v167, v185, v191
	v_fma_f32 v185, v167, v184, v192
	v_mov_b32_e32 v184, v193
	v_cvt_pk_bf16_f32 v194, v184, v185
	v_fma_f32 v191, v166, v184, v72
	ds_write_b16 v178, v194 offset:5632
	ds_write_b16_d16_hi v178, v194 offset:5760
	v_fma_f32 v192, v166, v185, v73
	v_fma_f32 v193, -v167, v185, v191
	v_fma_f32 v185, v167, v184, v192
	v_mov_b32_e32 v184, v193
	v_cvt_pk_bf16_f32 v194, v184, v185
	v_fma_f32 v191, v166, v184, v74
	ds_write_b16 v178, v194 offset:5120
	ds_write_b16_d16_hi v178, v194 offset:5248
	v_fma_f32 v192, v166, v185, v75
	v_fma_f32 v193, -v167, v185, v191
	v_fma_f32 v185, v167, v184, v192
	v_mov_b32_e32 v184, v193
	v_cvt_pk_bf16_f32 v194, v184, v185
	v_fma_f32 v191, v166, v184, v76
	ds_write_b16 v178, v194 offset:4608
	ds_write_b16_d16_hi v178, v194 offset:4736
	v_fma_f32 v192, v166, v185, v77
	v_fma_f32 v193, -v167, v185, v191
	v_fma_f32 v185, v167, v184, v192
	v_mov_b32_e32 v184, v193
	v_cvt_pk_bf16_f32 v194, v184, v185
	v_fma_f32 v191, v166, v184, v78
	ds_write_b16 v178, v194 offset:4096
	ds_write_b16_d16_hi v178, v194 offset:4224
	v_fma_f32 v192, v166, v185, v79
	v_fma_f32 v193, -v167, v185, v191
	v_fma_f32 v185, v167, v184, v192
	v_mov_b32_e32 v184, v193
	v_cvt_pk_bf16_f32 v194, v184, v185
	v_fma_f32 v191, v166, v184, v80
	ds_write_b16 v178, v194 offset:3584
	ds_write_b16_d16_hi v178, v194 offset:3712
	v_fma_f32 v192, v166, v185, v81
	v_fma_f32 v193, -v167, v185, v191
	v_fma_f32 v185, v167, v184, v192
	v_mov_b32_e32 v184, v193
	v_cvt_pk_bf16_f32 v194, v184, v185
	v_fma_f32 v191, v166, v184, v82
	ds_write_b16 v178, v194 offset:3072
	ds_write_b16_d16_hi v178, v194 offset:3200
	v_fma_f32 v192, v166, v185, v83
	v_fma_f32 v193, -v167, v185, v191
	v_fma_f32 v185, v167, v184, v192
	v_mov_b32_e32 v184, v193
	v_cvt_pk_bf16_f32 v194, v184, v185
	v_fma_f32 v191, v166, v184, v84
	ds_write_b16 v178, v194 offset:2560
	ds_write_b16_d16_hi v178, v194 offset:2688
	v_fma_f32 v192, v166, v185, v85
	v_fma_f32 v193, -v167, v185, v191
	v_fma_f32 v185, v167, v184, v192
	v_mov_b32_e32 v184, v193
	v_cvt_pk_bf16_f32 v194, v184, v185
	v_fma_f32 v191, v166, v184, v86
	ds_write_b16 v178, v194 offset:2048
	ds_write_b16_d16_hi v178, v194 offset:2176
	v_fma_f32 v192, v166, v185, v87
	v_fma_f32 v193, -v167, v185, v191
	v_fma_f32 v185, v167, v184, v192
	v_mov_b32_e32 v184, v193
	v_cvt_pk_bf16_f32 v194, v184, v185
	v_fma_f32 v191, v166, v184, v88
	ds_write_b16 v178, v194 offset:1536
	ds_write_b16_d16_hi v178, v194 offset:1664
	v_fma_f32 v192, v166, v185, v89
	v_fma_f32 v193, -v167, v185, v191
	v_fma_f32 v185, v167, v184, v192
	v_mov_b32_e32 v184, v193
	v_cvt_pk_bf16_f32 v194, v184, v185
	v_fma_f32 v191, v166, v184, v90
	ds_write_b16 v178, v194 offset:1024
	ds_write_b16_d16_hi v178, v194 offset:1152
	v_fma_f32 v192, v166, v185, v91
	v_fma_f32 v193, -v167, v185, v191
	v_fma_f32 v185, v167, v184, v192
	v_mov_b32_e32 v184, v193
	v_cvt_pk_bf16_f32 v194, v184, v185
	v_fma_f32 v191, v166, v184, v92
	ds_write_b16 v178, v194 offset:512
	ds_write_b16_d16_hi v178, v194 offset:640
	v_fma_f32 v192, v166, v185, v93
	v_fma_f32 v193, -v167, v185, v191
	v_fma_f32 v185, v167, v184, v192
	v_mov_b32_e32 v184, v193
	v_cvt_pk_bf16_f32 v194, v184, v185
	v_fma_f32 v191, v166, v184, v94
	ds_write_b16 v178, v194
	ds_write_b16_d16_hi v178, v194 offset:128
	v_fma_f32 v192, v166, v185, v95
	v_fma_f32 v193, -v167, v185, v191
	v_fma_f32 v185, v167, v184, v192
	v_mov_b32_e32 v184, v193
	v_cvt_pk_bf16_f32 v194, v186, v187
	v_fma_f32 v191, v166, v186, v96
	ds_write_b16 v179, v194 offset:7680
	ds_write_b16_d16_hi v179, v194 offset:7808
	v_fma_f32 v192, v166, v187, v97
	v_fma_f32 v193, -v167, v187, v191
	v_fma_f32 v187, v167, v186, v192
	v_mov_b32_e32 v186, v193
	v_cvt_pk_bf16_f32 v194, v186, v187
	v_fma_f32 v191, v166, v186, v98
	ds_write_b16 v179, v194 offset:7168
	ds_write_b16_d16_hi v179, v194 offset:7296
	v_fma_f32 v192, v166, v187, v99
	v_fma_f32 v193, -v167, v187, v191
	v_fma_f32 v187, v167, v186, v192
	v_mov_b32_e32 v186, v193
	v_cvt_pk_bf16_f32 v194, v186, v187
	v_fma_f32 v191, v166, v186, v100
	ds_write_b16 v179, v194 offset:6656
	ds_write_b16_d16_hi v179, v194 offset:6784
	v_fma_f32 v192, v166, v187, v101
	v_fma_f32 v193, -v167, v187, v191
	v_fma_f32 v187, v167, v186, v192
	v_mov_b32_e32 v186, v193
	v_cvt_pk_bf16_f32 v194, v186, v187
	v_fma_f32 v191, v166, v186, v102
	ds_write_b16 v179, v194 offset:6144
	ds_write_b16_d16_hi v179, v194 offset:6272
	v_fma_f32 v192, v166, v187, v103
	v_fma_f32 v193, -v167, v187, v191
	v_fma_f32 v187, v167, v186, v192
	v_mov_b32_e32 v186, v193
	v_cvt_pk_bf16_f32 v194, v186, v187
	v_fma_f32 v191, v166, v186, v104
	ds_write_b16 v179, v194 offset:5632
; __device__ __forceinline__ unsigned f2bf(float f) { unsigned u = __float_as_uint(f); return (u + 0x7fffu + ((u >> 16) & 1u)) >> 16; }
; __device__ __forceinline__ void s5_scan_bg(LAS unsigned char* lds, const S5In P, const bf16_t* F, bf16_t* XB, int b, int g, const int tid) {
;     ...
;     for (int jj = 0; jj < 4; ++jj) { const int job = wid + 8 * jj, di = job >> 4, seg = job & 15;
;         const float ar = di ? a1r[1] : a1r[0], ai = di ? a1i[1] : a1i[0]; const f32x2v x0 = XI[(di * 16 + seg) * 64 + p]; float xr = x0.x, xi = x0.y;
;         bf16_t* xg = XB + ((size_t)g * 1024 + b * 256) * 256 + di * 128 + p;
; #pragma unroll
;         for (int j = 0; j < 16; ++j) { const int c = di == 0 ? seg * 16 + j : 255 - (seg * 16 + j);
;             xg[(size_t)c * 256] = (bf16_t)f2bf(xr); xg[(size_t)c * 256 + 64] = (bf16_t)f2bf(xi);
;             const float nxr = ar * xr - ai * xi + fr[jj][j], nxi = ar * xi + ai * xr + fi[jj][j]; xr = nxr; xi = nxi; } }
;     __syncthreads();
	ds_write_b16_d16_hi v179, v194 offset:5760
	v_fma_f32 v192, v166, v187, v105
	v_fma_f32 v193, -v167, v187, v191
	v_fma_f32 v187, v167, v186, v192
	v_mov_b32_e32 v186, v193
	v_cvt_pk_bf16_f32 v194, v186, v187
	v_fma_f32 v191, v166, v186, v106
	ds_write_b16 v179, v194 offset:5120
	ds_write_b16_d16_hi v179, v194 offset:5248
	v_fma_f32 v192, v166, v187, v107
	v_fma_f32 v193, -v167, v187, v191
	v_fma_f32 v187, v167, v186, v192
	v_mov_b32_e32 v186, v193
	v_cvt_pk_bf16_f32 v194, v186, v187
	v_fma_f32 v191, v166, v186, v108
	ds_write_b16 v179, v194 offset:4608
	ds_write_b16_d16_hi v179, v194 offset:4736
	v_fma_f32 v192, v166, v187, v109
	v_fma_f32 v193, -v167, v187, v191
	v_fma_f32 v187, v167, v186, v192
	v_mov_b32_e32 v186, v193
	v_cvt_pk_bf16_f32 v194, v186, v187
	v_fma_f32 v191, v166, v186, v110
	ds_write_b16 v179, v194 offset:4096
	ds_write_b16_d16_hi v179, v194 offset:4224
	v_fma_f32 v192, v166, v187, v111
	v_fma_f32 v193, -v167, v187, v191
	v_fma_f32 v187, v167, v186, v192
	v_mov_b32_e32 v186, v193
	v_cvt_pk_bf16_f32 v194, v186, v187
	v_fma_f32 v191, v166, v186, v112
	ds_write_b16 v179, v194 offset:3584
	ds_write_b16_d16_hi v179, v194 offset:3712
	v_fma_f32 v192, v166, v187, v113
	v_fma_f32 v193, -v167, v187, v191
	v_fma_f32 v187, v167, v186, v192
	v_mov_b32_e32 v186, v193
	v_cvt_pk_bf16_f32 v194, v186, v187
	v_fma_f32 v191, v166, v186, v114
	ds_write_b16 v179, v194 offset:3072
	ds_write_b16_d16_hi v179, v194 offset:3200
	v_fma_f32 v192, v166, v187, v115
	v_fma_f32 v193, -v167, v187, v191
	v_fma_f32 v187, v167, v186, v192
	v_mov_b32_e32 v186, v193
	v_cvt_pk_bf16_f32 v194, v186, v187
	v_fma_f32 v191, v166, v186, v116
	ds_write_b16 v179, v194 offset:2560
	ds_write_b16_d16_hi v179, v194 offset:2688
	v_fma_f32 v192, v166, v187, v117
	v_fma_f32 v193, -v167, v187, v191
	v_fma_f32 v187, v167, v186, v192
	v_mov_b32_e32 v186, v193
	v_cvt_pk_bf16_f32 v194, v186, v187
	v_fma_f32 v191, v166, v186, v118
	ds_write_b16 v179, v194 offset:2048
	ds_write_b16_d16_hi v179, v194 offset:2176
	v_fma_f32 v192, v166, v187, v119
	v_fma_f32 v193, -v167, v187, v191
	v_fma_f32 v187, v167, v186, v192
	v_mov_b32_e32 v186, v193
	v_cvt_pk_bf16_f32 v194, v186, v187
	v_fma_f32 v191, v166, v186, v120
	ds_write_b16 v179, v194 offset:1536
	ds_write_b16_d16_hi v179, v194 offset:1664
	v_fma_f32 v192, v166, v187, v121
	v_fma_f32 v193, -v167, v187, v191
	v_fma_f32 v187, v167, v186, v192
	v_mov_b32_e32 v186, v193
	v_cvt_pk_bf16_f32 v194, v186, v187
	v_fma_f32 v191, v166, v186, v122
	ds_write_b16 v179, v194 offset:1024
	ds_write_b16_d16_hi v179, v194 offset:1152
	v_fma_f32 v192, v166, v187, v123
	v_fma_f32 v193, -v167, v187, v191
	v_fma_f32 v187, v167, v186, v192
	v_mov_b32_e32 v186, v193
	v_cvt_pk_bf16_f32 v194, v186, v187
	v_fma_f32 v191, v166, v186, v124
	ds_write_b16 v179, v194 offset:512
	ds_write_b16_d16_hi v179, v194 offset:640
	v_fma_f32 v192, v166, v187, v125
	v_fma_f32 v193, -v167, v187, v191
	v_fma_f32 v187, v167, v186, v192
	v_mov_b32_e32 v186, v193
	v_cvt_pk_bf16_f32 v194, v186, v187
	v_fma_f32 v191, v166, v186, v126
	ds_write_b16 v179, v194
	ds_write_b16_d16_hi v179, v194 offset:128
	v_fma_f32 v192, v166, v187, v127
	v_fma_f32 v193, -v167, v187, v191
	v_fma_f32 v187, v167, v186, v192
	v_mov_b32_e32 v186, v193
	s_waitcnt lgkmcnt(0)
	s_barrier
	v_lshlrev_b32_e32 v161, 4, v160
	v_add_u32_e32 v161, s27, v161
	ds_read_b128 v[0:3], v161
	ds_read_b128 v[4:7], v161 offset:1024
	ds_read_b128 v[8:11], v161 offset:2048
	ds_read_b128 v[12:15], v161 offset:3072
	s_waitcnt lgkmcnt(0)
	global_store_dwordx4 v161, v[0:3], s[24:25]
	global_store_dwordx4 v161, v[4:7], s[24:25] offset:1024
	global_store_dwordx4 v161, v[8:11], s[24:25] offset:2048
	global_store_dwordx4 v161, v[12:15], s[24:25] offset:3072
	s_nop 1
	v_add_u32_e32 v161, 0x1000, v161
	ds_read_b128 v[0:3], v161
	ds_read_b128 v[4:7], v161 offset:1024
	ds_read_b128 v[8:11], v161 offset:2048
	ds_read_b128 v[12:15], v161 offset:3072
	s_waitcnt lgkmcnt(0)
	global_store_dwordx4 v161, v[0:3], s[24:25]
	global_store_dwordx4 v161, v[4:7], s[24:25] offset:1024
	global_store_dwordx4 v161, v[8:11], s[24:25] offset:2048
	global_store_dwordx4 v161, v[12:15], s[24:25] offset:3072
	s_nop 1
	v_add_u32_e32 v161, 0x1000, v161
	ds_read_b128 v[0:3], v161
	ds_read_b128 v[4:7], v161 offset:1024
	ds_read_b128 v[8:11], v161 offset:2048
	ds_read_b128 v[12:15], v161 offset:3072
	s_waitcnt lgkmcnt(0)
	global_store_dwordx4 v161, v[0:3], s[24:25]
	global_store_dwordx4 v161, v[4:7], s[24:25] offset:1024
	global_store_dwordx4 v161, v[8:11], s[24:25] offset:2048
	global_store_dwordx4 v161, v[12:15], s[24:25] offset:3072
	s_nop 1
	v_add_u32_e32 v161, 0x1000, v161
	ds_read_b128 v[0:3], v161
	ds_read_b128 v[4:7], v161 offset:1024
	ds_read_b128 v[8:11], v161 offset:2048
	ds_read_b128 v[12:15], v161 offset:3072
	s_waitcnt lgkmcnt(0)
	global_store_dwordx4 v161, v[0:3], s[24:25]
	global_store_dwordx4 v161, v[4:7], s[24:25] offset:1024
	global_store_dwordx4 v161, v[8:11], s[24:25] offset:2048
	global_store_dwordx4 v161, v[12:15], s[24:25] offset:3072
	s_nop 1
	s_branch .LBB0_820
